# attention MODE0 loop: accumulate in place (no 64-reg copy in/out per tile), cross-half max via permlane32_swap
# speedup vs baseline: 1.0087x; 1.0049x over previous
; #define LAS __attribute__((address_space(3)))
; __device__ __forceinline__ void attn_item(const P& p, Frame& F, const bool is_s, const int b, const int g, const int c) {
;     ...
;             int tid = F.tid; asm volatile("" : "+v"(tid));
;             const bool loader = is_s && tid >= 256;
;             const int boff = (is_s || mode == 0) ? (i & 1) * A_BUF2 : 0;
;             if (is_s) {
;                 if (i == 0) { __syncthreads(); if (loader) loader_stage(F, kp, vp, pitch, mode == 1, nvalid, tid - 256, 0); }
;                 __syncthreads();
;                 if (loader && i + 1 < ntiles) { const void* kp1; const void* vp1; int pitch1, nv1; bool f1; SAMPLE_TILE(i + 1, kp1, vp1, pitch1, f1, nv1); loader_stage(F, kp1, vp1, pitch1, f1, nv1, tid - 256, ((i + 1) & 1) * A_BUF2); }
;             } else if (mode == 0) {
;                 if (i == 0) { __syncthreads(); tile_load(tr, (const bf16*)kp, (const bf16*)vp, pitch, tid); tile_store(F, tr, tid, 0); if (ntiles > 1) tile_load(tr, (const bf16*)kp + (size_t)64 * pitch, (const bf16*)vp + 128 * 64, pitch, tid); }
;                 __syncthreads();
;                 if (i + 1 < ntiles) { tile_store(F, tr, tid, ((i + 1) & 1) * A_BUF2); if (i + 2 < ntiles) tile_load(tr, (const bf16*)kp + (size_t)128 * pitch, (const bf16*)vp + 2 * 128 * 64, pitch, tid); }
;             } else if (!(ph == 1 && !is_s)) {
;                 __syncthreads();
;                 stage_tile(F, kp, vp, pitch, mode == 1, nvalid);
;                 __syncthreads();
;             }
;             const bool far = nvalid == 64 && kstride == 1 && (t_lo - (kp0 + 63) >= 1023) && (t_lo + 31 - kp0 < wl);
;             const bool interior = !is_s && nvalid == 64 && kstride == 1 && (kp0 + 63 <= t_lo) && (t_lo + 31 - kp0 < wl);
;             if (loader) continue;
;             if (ph == 1) { LAS float* imp_row = IMP + (is_s ? (hh * 4 + (ql & 3)) * 132 : (hh * 64 + iq) * 33); tile_compute<1>(F, boff, btab, qf, t, lv, kp0, kstride, nvalid, wl, far, interior, m, l, ot, invl, imp_row, 32 * i, qvalid); }
;             else tile_compute<0>(F, boff, btab, qf, t, lv, kp0, kstride, nvalid, wl, far, interior, m, l, ot, 0.f, nullptr, 0, false);
.LBB0_2105:
	s_and_b64 s[14:15], s[60:61], s[96:97]
	v_add_u32_e32 v16, 63, v1
	s_xor_b64 s[14:15], s[14:15], -1
	v_cmp_gt_i32_e32 vcc, v16, v232
	s_or_b64 s[14:15], s[14:15], vcc
	v_cmp_le_i32_e32 vcc, s85, v2
	s_xor_b64 s[10:11], s[6:7], -1
	s_or_b64 s[14:15], s[14:15], vcc
	s_or_b64 s[26:27], s[8:9], s[94:95]
	s_bitcmp1_b32 s33, 0
	s_cselect_b64 s[46:47], -1, 0
	s_and_b64 s[26:27], s[26:27], s[46:47]
	s_and_b64 s[26:27], s[26:27], exec
	s_cselect_b32 s26, 0x19f00, 0
	s_mov_b64 s[6:7], -1
	v_add_u32_e32 v2, s26, v237
	s_and_b64 vcc, exec, s[40:41]
	s_mul_i32 s44, s25, -3
	v_add_u32_e32 v242, v229, v1
	s_mul_i32 s96, s25, -6
	s_mul_i32 s97, s25, -5
	s_cbranch_vccz .LBB0_2124
	v_add_u32_e32 v244, s26, v236
	s_lshl_b32 s6, s25, 1
	s_lshl_b32 s7, s25, 3
	s_lshl_b32 s62, s25, 4
	s_mov_b32 s63, 0
	s_mov_b64 s[46:47], -1
	v_mov_b32_e32 v245, v241
	v_mov_b32_e32 v243, v240

; template <int MODE> ...
;     ...
;         if (MODE == 0) {
;             mloc = fmaxf(mloc, __shfl_xor(mloc, 32));
;             const float mnew = mloc > m + 8.0f ? mloc : m;
;             if (__ballot(mnew != m) != 0ull) { const float alpha = __builtin_amdgcn_exp2f(m - mnew); m = mnew; l *= alpha;
; #pragma unroll
;                 for (int dt = 0; dt < 4; ++dt)
; #pragma unroll
;                     for (int i = 0; i < 16; ++i) ot[dt][i] *= alpha; }
.LBB0_2115:
	s_or_b64 exec, exec, s[70:71]
	s_nop 5
	v_mov_b32_e32 v146, v246
	v_add_f32_e32 v148, 0x41000000, v245
	s_nop 0
	v_permlane32_swap_b32_e32 v146, v246
	v_max_f32_e32 v146, v146, v246
	v_cmp_gt_f32_e32 vcc, v146, v148
	s_nop 1
	v_cndmask_b32_e32 v146, v245, v146, vcc
	v_cmp_neq_f32_e32 vcc, v146, v245
	s_cbranch_vccz .LBB0_2117
	v_sub_f32_e32 v147, v245, v146
	v_exp_f32_e32 v148, v147
	s_nop 0
	v_mul_f32_e32 v243, v243, v148
	v_pk_mul_f32 v[80:81], v[80:81], v[148:149] op_sel_hi:[1,0]
	v_pk_mul_f32 v[78:79], v[78:79], v[148:149] op_sel_hi:[1,0]
	v_pk_mul_f32 v[76:77], v[76:77], v[148:149] op_sel_hi:[1,0]
	v_pk_mul_f32 v[74:75], v[74:75], v[148:149] op_sel_hi:[1,0]
	v_pk_mul_f32 v[72:73], v[72:73], v[148:149] op_sel_hi:[1,0]
	v_pk_mul_f32 v[70:71], v[70:71], v[148:149] op_sel_hi:[1,0]
	v_pk_mul_f32 v[68:69], v[68:69], v[148:149] op_sel_hi:[1,0]
	v_pk_mul_f32 v[66:67], v[66:67], v[148:149] op_sel_hi:[1,0]
	v_pk_mul_f32 v[64:65], v[64:65], v[148:149] op_sel_hi:[1,0]
	v_pk_mul_f32 v[62:63], v[62:63], v[148:149] op_sel_hi:[1,0]
	v_pk_mul_f32 v[60:61], v[60:61], v[148:149] op_sel_hi:[1,0]
	v_pk_mul_f32 v[58:59], v[58:59], v[148:149] op_sel_hi:[1,0]
	v_pk_mul_f32 v[56:57], v[56:57], v[148:149] op_sel_hi:[1,0]
	v_pk_mul_f32 v[54:55], v[54:55], v[148:149] op_sel_hi:[1,0]
	v_pk_mul_f32 v[52:53], v[52:53], v[148:149] op_sel_hi:[1,0]
	v_pk_mul_f32 v[50:51], v[50:51], v[148:149] op_sel_hi:[1,0]
	v_pk_mul_f32 v[48:49], v[48:49], v[148:149] op_sel_hi:[1,0]
	v_pk_mul_f32 v[46:47], v[46:47], v[148:149] op_sel_hi:[1,0]
	v_pk_mul_f32 v[44:45], v[44:45], v[148:149] op_sel_hi:[1,0]
	v_pk_mul_f32 v[42:43], v[42:43], v[148:149] op_sel_hi:[1,0]
	v_pk_mul_f32 v[40:41], v[40:41], v[148:149] op_sel_hi:[1,0]
	v_pk_mul_f32 v[38:39], v[38:39], v[148:149] op_sel_hi:[1,0]
	v_pk_mul_f32 v[36:37], v[36:37], v[148:149] op_sel_hi:[1,0]
	v_pk_mul_f32 v[34:35], v[34:35], v[148:149] op_sel_hi:[1,0]
	v_pk_mul_f32 v[32:33], v[32:33], v[148:149] op_sel_hi:[1,0]
	v_pk_mul_f32 v[30:31], v[30:31], v[148:149] op_sel_hi:[1,0]
	v_pk_mul_f32 v[28:29], v[28:29], v[148:149] op_sel_hi:[1,0]
	v_pk_mul_f32 v[26:27], v[26:27], v[148:149] op_sel_hi:[1,0]
	v_pk_mul_f32 v[24:25], v[24:25], v[148:149] op_sel_hi:[1,0]
	v_pk_mul_f32 v[22:23], v[22:23], v[148:149] op_sel_hi:[1,0]
	v_pk_mul_f32 v[20:21], v[20:21], v[148:149] op_sel_hi:[1,0]
	v_pk_mul_f32 v[18:19], v[18:19], v[148:149] op_sel_hi:[1,0]
	s_branch .LBB0_2118

; #define LAS __attribute__((address_space(3)))
; __device__ __forceinline__ unsigned pk2(float lo, float hi) { const bfx2 b = __builtin_convertvector((f32x2){lo, hi}, bfx2); return __builtin_bit_cast(unsigned, b); }
; #define MFMA32(a, b, c) __builtin_amdgcn_mfma_f32_32x32x16_bf16((a), (b), (c), 0, 0, 0)
; template <int MODE> ...
;     ...
;             float ls = 0.f; const float meff = lanevalid ? m : 3.0e30f;
; #pragma unroll
;             for (int r = 0; r < 16; ++r) { const float pv = __builtin_amdgcn_exp2f(st[r] - meff); st[r] = pv; ls += pv; }
;             l += ls;
; #pragma unroll
;             for (int s = 0; s < 2; ++s) {
;                 u32x4 pb; pb.x = pk2(st[8 * s + 0], st[8 * s + 1]); pb.y = pk2(st[8 * s + 2], st[8 * s + 3]); pb.z = pk2(st[8 * s + 4], st[8 * s + 5]); pb.w = pk2(st[8 * s + 6], st[8 * s + 7]);
;                 const bf16x8 bfrag = __builtin_bit_cast(bf16x8, pb);
;                 const LAS unsigned char* va = VT + ql * VT_PITCH + (32 * nt + 16 * s + 4 * half) * 2;
;                 s16x4 lo[4], hi[4];
; #pragma unroll
;                 for (int dt = 0; dt < 4; ++dt) { lo[dt] = *(const LAS s16x4*)(va + 32 * dt * VT_PITCH); hi[dt] = *(const LAS s16x4*)(va + 32 * dt * VT_PITCH + 16); }
; #pragma unroll
;                 for (int dt = 0; dt < 4; ++dt) { const bf16x8 afrag = __builtin_shufflevector(lo[dt], hi[dt], 0, 1, 2, 3, 4, 5, 6, 7); ot[dt] = MFMA32(afrag, bfrag, ot[dt]); }
;             }
.LBB0_2118:
	v_cndmask_b32_e64 v147, v225, v146, s[74:75]
	v_sub_f32_e32 v148, v206, v147
	v_exp_f32_e32 v160, v148
	v_sub_f32_e32 v148, v207, v147
	v_exp_f32_e32 v161, v148
	v_sub_f32_e32 v148, v210, v147
	v_sub_f32_e32 v152, v208, v147
	v_lshl_add_u32 v208, s63, 6, v244
	v_exp_f32_e32 v206, v148
	v_sub_f32_e32 v148, v211, v147
	v_add_u32_e32 v210, 0x4000, v208
	v_exp_f32_e32 v207, v148
	ds_read2_b64 v[148:151], v210 offset0:128 offset1:130
	v_sub_f32_e32 v16, v16, v147
	v_sub_f32_e32 v17, v17, v147
	v_exp_f32_e32 v211, v152
	v_sub_f32_e32 v152, v209, v147
	v_exp_f32_e32 v16, v16
	v_exp_f32_e32 v17, v17
	v_exp_f32_e32 v209, v152
	v_cvt_pk_bf16_f32 v153, v160, v161
	v_cvt_pk_bf16_f32 v154, v206, v207
	v_cvt_pk_bf16_f32 v152, v16, v17
	v_cvt_pk_bf16_f32 v155, v211, v209
	v_add_u32_e32 v245, 0x5000, v208
	v_sub_f32_e32 v156, v212, v147
	s_waitcnt lgkmcnt(0)
	v_mfma_f32_32x32x16_bf16 v[66:81], v[148:151], v[152:155], v[66:81]
	ds_read2_b64 v[148:151], v245 offset0:160 offset1:162
	v_add_u32_e32 v246, 0x6000, v208
	v_exp_f32_e32 v212, v156
	ds_read2_b64 v[156:159], v246 offset0:192 offset1:194
	v_add_u32_e32 v208, 0x7000, v208
	v_sub_f32_e32 v215, v215, v147
	v_sub_f32_e32 v218, v218, v147
	s_waitcnt lgkmcnt(1)
	v_mfma_f32_32x32x16_bf16 v[50:65], v[148:151], v[152:155], v[50:65]
	v_sub_f32_e32 v148, v213, v147
	v_exp_f32_e32 v213, v148
	v_sub_f32_e32 v148, v214, v147
	v_exp_f32_e32 v214, v148
	ds_read2_b64 v[148:151], v208 offset0:224 offset1:226
	v_exp_f32_e32 v215, v215
	v_add_f32_e32 v16, 0, v16
	s_waitcnt lgkmcnt(1)
	v_mfma_f32_32x32x16_bf16 v[34:49], v[156:159], v[152:155], v[34:49]
	v_sub_f32_e32 v156, v216, v147
	v_exp_f32_e32 v216, v156
	v_sub_f32_e32 v156, v217, v147
	v_exp_f32_e32 v217, v156
	ds_read2_b64 v[156:159], v210 offset0:132 offset1:134
	v_sub_f32_e32 v147, v219, v147
	v_exp_f32_e32 v210, v218
	s_waitcnt lgkmcnt(1)
	v_mfma_f32_32x32x16_bf16 v[18:33], v[148:151], v[152:155], v[18:33]
	ds_read2_b64 v[152:155], v245 offset0:164 offset1:166
	v_exp_f32_e32 v147, v147
	v_cvt_pk_bf16_f32 v148, v212, v213
	v_cvt_pk_bf16_f32 v149, v214, v215
	v_cvt_pk_bf16_f32 v150, v216, v217
	v_cvt_pk_bf16_f32 v151, v210, v147
	v_add_f32_e32 v16, v17, v16
	v_add_f32_e32 v16, v160, v16
	s_waitcnt lgkmcnt(1)
	v_mfma_f32_32x32x16_bf16 v[66:81], v[156:159], v[148:151], v[66:81]
	ds_read2_b64 v[156:159], v246 offset0:196 offset1:198
	v_add_f32_e32 v16, v161, v16
	v_add_f32_e32 v16, v206, v16
	v_add_f32_e32 v16, v207, v16
	v_add_f32_e32 v16, v211, v16
	v_add_f32_e32 v16, v209, v16
	v_add_f32_e32 v16, v212, v16
	s_waitcnt lgkmcnt(1)
	v_mfma_f32_32x32x16_bf16 v[50:65], v[152:155], v[148:151], v[50:65]
	ds_read2_b64 v[152:155], v208 offset0:228 offset1:230
	v_add_f32_e32 v16, v213, v16
	v_add_f32_e32 v16, v214, v16
	v_add_f32_e32 v16, v215, v16
	v_add_f32_e32 v16, v216, v16
	v_add_f32_e32 v16, v217, v16
	v_add_f32_e32 v16, v210, v16
	s_waitcnt lgkmcnt(1)
	v_mfma_f32_32x32x16_bf16 v[34:49], v[156:159], v[148:151], v[34:49]
	v_add_f32_e32 v16, v147, v16
	s_xor_b64 s[26:27], s[46:47], -1
	v_add_f32_e32 v243, v243, v16
	s_mov_b32 s63, 1
	s_andn2_b64 vcc, exec, s[26:27]
	s_mov_b64 s[46:47], 0
	s_waitcnt lgkmcnt(0)
	v_mfma_f32_32x32x16_bf16 v[18:33], v[152:155], v[148:151], v[18:33]
	s_cbranch_vccz .Lattn_m0_exit
	v_mov_b32_e32 v245, v146
	s_branch .LBB0_2107
.Lattn_m0_exit:
	s_nop 7
	s_branch .Lattn_m0_join

; __device__ __forceinline__ void attn_item(const P& p, Frame& F, const bool is_s, const int b, const int g, const int c) {
;     ...
;         for (int i = 0; i < ntiles; ++i) {
;     ...
;             else tile_compute<0>(F, boff, btab, qf, t, lv, kp0, kstride, nvalid, wl, far, interior, m, l, ot, 0.f, nullptr, 0, false);
;         }
.Lattn_m0_join:
	v_mov_b32_e32 v241, v146
	v_mov_b32_e32 v240, v243
	s_or_b64 exec, exec, s[0:1]
	s_add_i32 s33, s33, 1
	s_cmp_eq_u32 s33, s2
	s_cbranch_scc1 .LBB0_2140
